# GLA scan output block split between the wave halves (waves 0-3 inter-chunk MFMAs + LDS partial, waves 4-7 intra-chunk MFMAs + add/convert/store after the second barrier)
# baseline (speedup 1.0000x reference)
.LBB0_473:
	s_waitcnt vmcnt(22)
	ds_write_b128 v202, v[52:55] offset:17408
	ds_write_b128 v202, v[48:51] offset:17424
	s_waitcnt vmcnt(20)
	ds_write_b128 v203, v[60:63] offset:34816
	ds_write_b128 v203, v[56:59] offset:34832
	s_waitcnt vmcnt(19)
	ds_write_b128 v204, v[64:67] offset:53248
	s_waitcnt vmcnt(18)
	ds_write_b16 v144, v96 offset:62464
	ds_write_b16_d16_hi v144, v96 offset:62608
	ds_write_b16 v144, v97 offset:62752
	ds_write_b16_d16_hi v144, v97 offset:62896
	ds_write_b16 v144, v98 offset:63040
	ds_write_b16_d16_hi v144, v98 offset:63184
	ds_write_b16 v144, v99 offset:63328
	ds_write_b16_d16_hi v144, v99 offset:63472
	s_and_saveexec_b64 s[50:51], s[0:1]
	ds_write_b32 v205, v199
	s_or_b64 exec, exec, s[50:51]
	s_waitcnt lgkmcnt(0)
	s_barrier
	s_and_saveexec_b64 s[50:51], s[4:5]
	s_cbranch_execz .Lss0_hi
	ds_read_b128 v[214:217], v206 offset:17408
	ds_read_b128 v[218:221], v207
	ds_read_b128 v[222:225], v206 offset:17440
	ds_read_b128 v[226:229], v207 offset:32
	ds_read_b128 v[240:243], v206 offset:17472
	ds_read_b128 v[244:247], v207 offset:64
	ds_read_b128 v[248:251], v206 offset:17504
	ds_read_b128 v[252:255], v207 offset:96
	s_waitcnt lgkmcnt(6)
	v_mfma_f32_32x32x16_bf16 v[32:47], v[214:217], v[218:221], 0
	ds_read_b128 v[214:217], v206 offset:17536
	ds_read_b128 v[218:221], v207 offset:128
	s_waitcnt lgkmcnt(6)
	v_mfma_f32_32x32x16_bf16 v[32:47], v[222:225], v[226:229], v[32:47]
	ds_read_b128 v[222:225], v206 offset:17568
	ds_read_b128 v[226:229], v207 offset:160
	s_waitcnt lgkmcnt(6)
	v_mfma_f32_32x32x16_bf16 v[32:47], v[240:243], v[244:247], v[32:47]
	ds_read_b128 v[240:243], v206 offset:17600
	ds_read_b128 v[244:247], v207 offset:192
	s_waitcnt lgkmcnt(6)
	v_mfma_f32_32x32x16_bf16 v[32:47], v[248:251], v[252:255], v[32:47]
	ds_read_b128 v[248:251], v206 offset:17632
	ds_read_b128 v[252:255], v207 offset:224
	s_waitcnt lgkmcnt(6)
	v_mfma_f32_32x32x16_bf16 v[32:47], v[214:217], v[218:221], v[32:47]
	s_waitcnt lgkmcnt(4)
	v_mfma_f32_32x32x16_bf16 v[32:47], v[222:225], v[226:229], v[32:47]
	s_waitcnt lgkmcnt(2)
	v_mfma_f32_32x32x16_bf16 v[32:47], v[240:243], v[244:247], v[32:47]
	s_waitcnt lgkmcnt(0)
	v_mfma_f32_32x32x16_bf16 v[32:47], v[248:251], v[252:255], v[32:47]
	v_and_b32_e32 v236, 0xff, v208
	v_lshlrev_b32_e32 v236, 4, v236
	v_add_u32_e32 v236, 0x18000, v236
	s_nop 11
	ds_write_b128 v236, v[32:35]
	ds_write_b128 v236, v[36:39] offset:4096
	ds_write_b128 v236, v[40:43] offset:8192
	ds_write_b128 v236, v[44:47] offset:12288
	s_branch .LBB0_477
.Lss0_hi:
	s_mov_b64 exec, s[50:51]
	s_add_i32 s10, s85, 0xfffffe40
	s_add_i32 s87, s86, 0x1c0
	s_and_b64 s[52:53], s[48:49], exec
	s_cselect_b32 s10, s10, s87
	s_add_u32 s52, s46, s10
	s_addc_u32 s53, 0, s47
	s_lshl_b64 s[98:99], s[52:53], 11
	ds_read_b128 v[214:217], v209 offset:53248
	ds_read_b128 v[218:221], v210 offset:62464
	ds_read_b128 v[222:225], v209 offset:53280
	ds_read_b128 v[226:229], v210 offset:62496
	ds_read_b128 v[16:19], v209 offset:53312
	ds_read_b128 v[20:23], v210 offset:62528
	ds_read_b128 v[24:27], v209 offset:53344
	ds_read_b128 v[28:31], v210 offset:62560
	s_waitcnt lgkmcnt(6)
	v_mfma_f32_32x32x16_bf16 v[240:255], v[214:217], v[218:221], 0
	s_waitcnt lgkmcnt(4)
	v_mfma_f32_32x32x16_bf16 v[240:255], v[222:225], v[226:229], v[240:255]
	s_waitcnt lgkmcnt(2)
	v_mfma_f32_32x32x16_bf16 v[240:255], v[16:19], v[20:23], v[240:255]
	s_waitcnt lgkmcnt(0)
	v_mfma_f32_32x32x16_bf16 v[240:255], v[24:27], v[28:31], v[240:255]
.LBB0_477:
	s_or_b64 exec, exec, s[50:51]
	ds_read_b128 v[16:19], v212 offset:96
	ds_read_b128 v[20:23], v212 offset:64
	ds_read_b128 v[24:27], v212 offset:32
	ds_read_b128 v[28:31], v212
	ds_read_b128 v[32:35], v211 offset:34816
	s_waitcnt lgkmcnt(4)
	v_pk_mul_f32 v[12:13], v[12:13], v[16:17]
	v_pk_mul_f32 v[14:15], v[14:15], v[18:19]
	ds_read_b128 v[16:19], v210 offset:62464
	s_waitcnt lgkmcnt(4)
	v_pk_mul_f32 v[8:9], v[8:9], v[20:21]
	s_waitcnt lgkmcnt(3)
	v_pk_mul_f32 v[4:5], v[4:5], v[24:25]
	s_waitcnt lgkmcnt(2)
	v_pk_mul_f32 v[0:1], v[0:1], v[28:29]
	v_pk_mul_f32 v[10:11], v[10:11], v[22:23]
	v_pk_mul_f32 v[6:7], v[6:7], v[26:27]
	v_pk_mul_f32 v[2:3], v[2:3], v[30:31]
	ds_read_b128 v[20:23], v211 offset:34848
	ds_read_b128 v[24:27], v210 offset:62496
	s_waitcnt lgkmcnt(2)
	v_mfma_f32_32x32x16_bf16 v[0:15], v[32:35], v[16:19], v[0:15]
	s_add_i32 s84, s84, 4
	s_cmp_gt_u32 s84, 59
	s_cselect_b64 s[50:51], -1, 0
	v_lshl_add_u64 v[196:197], s[92:93], 0, v[188:189]
	v_lshl_add_u64 v[192:193], s[92:93], 0, v[186:187]
	s_and_b64 vcc, exec, s[50:51]
	v_lshl_add_u64 v[194:195], s[94:95], 0, v[184:185]
	s_waitcnt lgkmcnt(0)
	v_mfma_f32_32x32x16_bf16 v[0:15], v[20:23], v[24:27], v[0:15]
	ds_read_b128 v[16:19], v211 offset:34880
	ds_read_b128 v[20:23], v210 offset:62528
	ds_read_b128 v[24:27], v211 offset:34912
	ds_read_b128 v[28:31], v210 offset:62560
	s_waitcnt lgkmcnt(0)
	s_barrier
	s_waitcnt lgkmcnt(2)
	v_mfma_f32_32x32x16_bf16 v[0:15], v[16:19], v[20:23], v[0:15]
	s_waitcnt lgkmcnt(0)
	v_mfma_f32_32x32x16_bf16 v[0:15], v[24:27], v[28:31], v[0:15]
	s_nop 11
	v_cvt_pk_bf16_f32 v16, v0, v1
	v_cvt_pk_bf16_f32 v17, v2, v3
	v_cvt_pk_bf16_f32 v18, v4, v5
	v_cvt_pk_bf16_f32 v19, v6, v7
	v_cvt_pk_bf16_f32 v20, v8, v9
	v_cvt_pk_bf16_f32 v21, v10, v11
	v_cvt_pk_bf16_f32 v22, v12, v13
	v_cvt_pk_bf16_f32 v23, v14, v15
	ds_write2_b64 v213, v[16:17], v[18:19] offset1:2
	ds_write2_b64 v213, v[20:21], v[22:23] offset0:4 offset1:6
	v_lshrrev_b32_e32 v236, 8, v208
	v_cmpx_ne_u32_e64 s[100:101], 0, v236
	s_cbranch_execz .Lss0_skip
	v_and_b32_e32 v236, 0xff, v208
	v_lshlrev_b32_e32 v236, 4, v236
	v_add_u32_e32 v236, 0x18000, v236
	ds_read_b128 v[214:217], v236
	ds_read_b128 v[218:221], v236 offset:4096
	ds_read_b128 v[222:225], v236 offset:8192
	ds_read_b128 v[226:229], v236 offset:12288
	s_waitcnt lgkmcnt(0)
	v_add_f32_e32 v236, v240, v214
	v_cvt_pk_bf16_f32 v236, v236, s0
	v_lshl_add_u64 v[24:25], s[98:99], 0, v[152:153]
	global_store_short v[24:25], v236, off
	v_add_f32_e32 v237, v241, v215
	v_cvt_pk_bf16_f32 v237, v237, s0
	v_lshl_add_u64 v[26:27], s[98:99], 0, v[154:155]
	global_store_short v[26:27], v237, off
	v_add_f32_e32 v236, v242, v216
	v_cvt_pk_bf16_f32 v236, v236, s0
	v_lshl_add_u64 v[24:25], s[98:99], 0, v[156:157]
	global_store_short v[24:25], v236, off
	v_add_f32_e32 v237, v243, v217
	v_cvt_pk_bf16_f32 v237, v237, s0
	v_lshl_add_u64 v[26:27], s[98:99], 0, v[158:159]
	global_store_short v[26:27], v237, off
	v_add_f32_e32 v236, v244, v218
	v_cvt_pk_bf16_f32 v236, v236, s0
	v_lshl_add_u64 v[24:25], s[98:99], 0, v[160:161]
	global_store_short v[24:25], v236, off
	v_add_f32_e32 v237, v245, v219
	v_cvt_pk_bf16_f32 v237, v237, s0
	v_lshl_add_u64 v[26:27], s[98:99], 0, v[162:163]
	global_store_short v[26:27], v237, off
	v_add_f32_e32 v236, v246, v220
	v_cvt_pk_bf16_f32 v236, v236, s0
	v_lshl_add_u64 v[24:25], s[98:99], 0, v[164:165]
	global_store_short v[24:25], v236, off
	v_add_f32_e32 v237, v247, v221
	v_cvt_pk_bf16_f32 v237, v237, s0
	v_lshl_add_u64 v[26:27], s[98:99], 0, v[166:167]
	global_store_short v[26:27], v237, off
	v_add_f32_e32 v236, v248, v222
	v_cvt_pk_bf16_f32 v236, v236, s0
	v_lshl_add_u64 v[24:25], s[98:99], 0, v[168:169]
	global_store_short v[24:25], v236, off
	v_add_f32_e32 v237, v249, v223
	v_cvt_pk_bf16_f32 v237, v237, s0
	v_lshl_add_u64 v[26:27], s[98:99], 0, v[170:171]
	global_store_short v[26:27], v237, off
	v_add_f32_e32 v236, v250, v224
	v_cvt_pk_bf16_f32 v236, v236, s0
	v_lshl_add_u64 v[24:25], s[98:99], 0, v[172:173]
	global_store_short v[24:25], v236, off
	v_add_f32_e32 v237, v251, v225
	v_cvt_pk_bf16_f32 v237, v237, s0
	v_lshl_add_u64 v[26:27], s[98:99], 0, v[174:175]
	global_store_short v[26:27], v237, off
	v_add_f32_e32 v236, v252, v226
	v_cvt_pk_bf16_f32 v236, v236, s0
	v_lshl_add_u64 v[24:25], s[98:99], 0, v[176:177]
	global_store_short v[24:25], v236, off
	v_add_f32_e32 v237, v253, v227
	v_cvt_pk_bf16_f32 v237, v237, s0
	v_lshl_add_u64 v[26:27], s[98:99], 0, v[178:179]
	global_store_short v[26:27], v237, off
	v_add_f32_e32 v236, v254, v228
	v_cvt_pk_bf16_f32 v236, v236, s0
	v_lshl_add_u64 v[24:25], s[98:99], 0, v[180:181]
	global_store_short v[24:25], v236, off
	v_add_f32_e32 v237, v255, v229
	v_cvt_pk_bf16_f32 v237, v237, s0
	v_lshl_add_u64 v[26:27], s[98:99], 0, v[182:183]
	global_store_short v[26:27], v237, off
.Lss0_skip:
	s_mov_b64 exec, -1
	s_cbranch_vccnz .LBB0_481
	v_add_co_u32_e32 v18, vcc, 0x8040000, v196
	v_lshl_add_u64 v[16:17], v[196:197], 0, s[24:25]
	s_nop 0
	v_addc_co_u32_e32 v19, vcc, 0, v197, vcc
	global_load_dwordx4 v[52:55], v[18:19], off
	global_load_dwordx4 v[48:51], v[16:17], off offset:16
	v_add_co_u32_e32 v18, vcc, 0xc010000, v192
	v_lshl_add_u64 v[16:17], v[192:193], 0, s[26:27]
	s_nop 0
	v_addc_co_u32_e32 v19, vcc, 0, v193, vcc
	global_load_dwordx4 v[60:63], v[18:19], off
	global_load_dwordx4 v[56:59], v[16:17], off offset:16
	v_add_co_u32_e32 v16, vcc, 0x6808000, v194
	s_nop 1
	v_addc_co_u32_e32 v17, vcc, 0, v195, vcc
	global_load_dwordx4 v[64:67], v[16:17], off
	s_and_saveexec_b64 s[52:53], s[0:1]
	s_cbranch_execz .LBB0_480
	v_lshl_add_u64 v[16:17], s[94:95], 0, v[190:191]
	global_load_dword v199, v[16:17], off offset:-1024

.Lsw0_join:
	ds_write_b16 v144, v120 offset:62464
	ds_write_b16_d16_hi v144, v120 offset:62608
	ds_write_b16 v144, v121 offset:62752
	ds_write_b16_d16_hi v144, v121 offset:62896
	ds_write_b16 v144, v122 offset:63040
	ds_write_b16_d16_hi v144, v122 offset:63184
	ds_write_b16 v144, v123 offset:63328
	ds_write_b16_d16_hi v144, v123 offset:63472
	s_and_saveexec_b64 s[52:53], s[0:1]
	ds_write_b32 v205, v198
	s_or_b64 exec, exec, s[52:53]
	s_waitcnt lgkmcnt(0)
	s_barrier
	s_and_saveexec_b64 s[52:53], s[4:5]
	s_cbranch_execz .Lss1_hi
	ds_read_b128 v[214:217], v206 offset:17408
	ds_read_b128 v[218:221], v207
	ds_read_b128 v[222:225], v206 offset:17440
	ds_read_b128 v[226:229], v207 offset:32
	ds_read_b128 v[240:243], v206 offset:17472
	ds_read_b128 v[244:247], v207 offset:64
	ds_read_b128 v[248:251], v206 offset:17504
	ds_read_b128 v[252:255], v207 offset:96
	s_waitcnt lgkmcnt(6)
	v_mfma_f32_32x32x16_bf16 v[32:47], v[214:217], v[218:221], 0
	ds_read_b128 v[214:217], v206 offset:17536
	ds_read_b128 v[218:221], v207 offset:128
	s_waitcnt lgkmcnt(6)
	v_mfma_f32_32x32x16_bf16 v[32:47], v[222:225], v[226:229], v[32:47]
	ds_read_b128 v[222:225], v206 offset:17568
	ds_read_b128 v[226:229], v207 offset:160
	s_waitcnt lgkmcnt(6)
	v_mfma_f32_32x32x16_bf16 v[32:47], v[240:243], v[244:247], v[32:47]
	ds_read_b128 v[240:243], v206 offset:17600
	ds_read_b128 v[244:247], v207 offset:192
	s_waitcnt lgkmcnt(6)
	v_mfma_f32_32x32x16_bf16 v[32:47], v[248:251], v[252:255], v[32:47]
	ds_read_b128 v[248:251], v206 offset:17632
	ds_read_b128 v[252:255], v207 offset:224
	s_waitcnt lgkmcnt(6)
	v_mfma_f32_32x32x16_bf16 v[32:47], v[214:217], v[218:221], v[32:47]
	s_waitcnt lgkmcnt(4)
	v_mfma_f32_32x32x16_bf16 v[32:47], v[222:225], v[226:229], v[32:47]
	s_waitcnt lgkmcnt(2)
	v_mfma_f32_32x32x16_bf16 v[32:47], v[240:243], v[244:247], v[32:47]
	s_waitcnt lgkmcnt(0)
	v_mfma_f32_32x32x16_bf16 v[32:47], v[248:251], v[252:255], v[32:47]
	v_and_b32_e32 v236, 0xff, v208
	v_lshlrev_b32_e32 v236, 4, v236
	v_add_u32_e32 v236, 0x18000, v236
	s_nop 11
	ds_write_b128 v236, v[32:35]
	ds_write_b128 v236, v[36:39] offset:4096
	ds_write_b128 v236, v[40:43] offset:8192
	ds_write_b128 v236, v[44:47] offset:12288
	s_branch .LBB0_485
.Lss1_hi:
	s_mov_b64 exec, s[52:53]
	s_add_i32 s10, s85, 0xfffffe80
	s_add_i32 s87, s86, 0x180
	s_and_b64 s[96:97], s[48:49], exec
	s_cselect_b32 s10, s10, s87
	s_add_u32 s96, s46, s10
	s_addc_u32 s97, 0, s47
	s_lshl_b64 s[98:99], s[96:97], 11
	ds_read_b128 v[214:217], v209 offset:53248
	ds_read_b128 v[218:221], v210 offset:62464
	ds_read_b128 v[222:225], v209 offset:53280
	ds_read_b128 v[226:229], v210 offset:62496
	ds_read_b128 v[16:19], v209 offset:53312
	ds_read_b128 v[20:23], v210 offset:62528
	ds_read_b128 v[24:27], v209 offset:53344
	ds_read_b128 v[28:31], v210 offset:62560
	s_waitcnt lgkmcnt(6)
	v_mfma_f32_32x32x16_bf16 v[240:255], v[214:217], v[218:221], 0
	s_waitcnt lgkmcnt(4)
	v_mfma_f32_32x32x16_bf16 v[240:255], v[222:225], v[226:229], v[240:255]
	s_waitcnt lgkmcnt(2)
	v_mfma_f32_32x32x16_bf16 v[240:255], v[16:19], v[20:23], v[240:255]
	s_waitcnt lgkmcnt(0)
	v_mfma_f32_32x32x16_bf16 v[240:255], v[24:27], v[28:31], v[240:255]
.LBB0_485:
	s_or_b64 exec, exec, s[52:53]
	ds_read_b128 v[16:19], v212 offset:96
	ds_read_b128 v[20:23], v212 offset:64
	ds_read_b128 v[24:27], v212 offset:32
	ds_read_b128 v[28:31], v212
	ds_read_b128 v[32:35], v211 offset:34816
	s_waitcnt lgkmcnt(4)
	v_pk_mul_f32 v[12:13], v[12:13], v[16:17]
	v_pk_mul_f32 v[14:15], v[14:15], v[18:19]
	ds_read_b128 v[16:19], v210 offset:62464
	s_waitcnt lgkmcnt(4)
	v_pk_mul_f32 v[8:9], v[8:9], v[20:21]
	s_waitcnt lgkmcnt(3)
	v_pk_mul_f32 v[4:5], v[4:5], v[24:25]
	v_pk_mul_f32 v[10:11], v[10:11], v[22:23]
	v_pk_mul_f32 v[6:7], v[6:7], v[26:27]
	s_waitcnt lgkmcnt(2)
	v_pk_mul_f32 v[2:3], v[2:3], v[30:31]
	v_pk_mul_f32 v[0:1], v[0:1], v[28:29]
	ds_read_b128 v[20:23], v211 offset:34848
	ds_read_b128 v[24:27], v210 offset:62496
	s_waitcnt lgkmcnt(2)
	v_mfma_f32_32x32x16_bf16 v[0:15], v[32:35], v[16:19], v[0:15]
	s_cmp_gt_u32 s84, 58
	s_waitcnt lgkmcnt(0)
	v_mfma_f32_32x32x16_bf16 v[0:15], v[20:23], v[24:27], v[0:15]
	ds_read_b128 v[16:19], v211 offset:34880
	ds_read_b128 v[20:23], v210 offset:62528
	ds_read_b128 v[24:27], v211 offset:34912
	ds_read_b128 v[28:31], v210 offset:62560
	s_waitcnt lgkmcnt(0)
	s_barrier
	s_waitcnt lgkmcnt(2)
	v_mfma_f32_32x32x16_bf16 v[0:15], v[16:19], v[20:23], v[0:15]
	s_waitcnt lgkmcnt(0)
	v_mfma_f32_32x32x16_bf16 v[0:15], v[24:27], v[28:31], v[0:15]
	s_nop 11
	v_cvt_pk_bf16_f32 v16, v0, v1
	v_cvt_pk_bf16_f32 v17, v2, v3
	v_cvt_pk_bf16_f32 v18, v4, v5
	v_cvt_pk_bf16_f32 v19, v6, v7
	v_cvt_pk_bf16_f32 v20, v8, v9
	v_cvt_pk_bf16_f32 v21, v10, v11
	v_cvt_pk_bf16_f32 v22, v12, v13
	v_cvt_pk_bf16_f32 v23, v14, v15
	ds_write2_b64 v213, v[16:17], v[18:19] offset1:2
	ds_write2_b64 v213, v[20:21], v[22:23] offset0:4 offset1:6
	v_lshrrev_b32_e32 v236, 8, v208
	v_cmpx_ne_u32_e64 s[100:101], 0, v236
	s_cbranch_execz .Lss1_skip
	v_and_b32_e32 v236, 0xff, v208
	v_lshlrev_b32_e32 v236, 4, v236
	v_add_u32_e32 v236, 0x18000, v236
	ds_read_b128 v[214:217], v236
	ds_read_b128 v[218:221], v236 offset:4096
	ds_read_b128 v[222:225], v236 offset:8192
	ds_read_b128 v[226:229], v236 offset:12288
	s_waitcnt lgkmcnt(0)
	v_add_f32_e32 v236, v240, v214
	v_cvt_pk_bf16_f32 v236, v236, s0
	v_lshl_add_u64 v[24:25], s[98:99], 0, v[152:153]
	global_store_short v[24:25], v236, off
	v_add_f32_e32 v237, v241, v215
	v_cvt_pk_bf16_f32 v237, v237, s0
	v_lshl_add_u64 v[26:27], s[98:99], 0, v[154:155]
	global_store_short v[26:27], v237, off
	v_add_f32_e32 v236, v242, v216
	v_cvt_pk_bf16_f32 v236, v236, s0
	v_lshl_add_u64 v[24:25], s[98:99], 0, v[156:157]
	global_store_short v[24:25], v236, off
	v_add_f32_e32 v237, v243, v217
	v_cvt_pk_bf16_f32 v237, v237, s0
	v_lshl_add_u64 v[26:27], s[98:99], 0, v[158:159]
	global_store_short v[26:27], v237, off
	v_add_f32_e32 v236, v244, v218
	v_cvt_pk_bf16_f32 v236, v236, s0
	v_lshl_add_u64 v[24:25], s[98:99], 0, v[160:161]
	global_store_short v[24:25], v236, off
	v_add_f32_e32 v237, v245, v219
	v_cvt_pk_bf16_f32 v237, v237, s0
	v_lshl_add_u64 v[26:27], s[98:99], 0, v[162:163]
	global_store_short v[26:27], v237, off
	v_add_f32_e32 v236, v246, v220
	v_cvt_pk_bf16_f32 v236, v236, s0
	v_lshl_add_u64 v[24:25], s[98:99], 0, v[164:165]
	global_store_short v[24:25], v236, off
	v_add_f32_e32 v237, v247, v221
	v_cvt_pk_bf16_f32 v237, v237, s0
	v_lshl_add_u64 v[26:27], s[98:99], 0, v[166:167]
	global_store_short v[26:27], v237, off
	v_add_f32_e32 v236, v248, v222
	v_cvt_pk_bf16_f32 v236, v236, s0
	v_lshl_add_u64 v[24:25], s[98:99], 0, v[168:169]
	global_store_short v[24:25], v236, off
	v_add_f32_e32 v237, v249, v223
	v_cvt_pk_bf16_f32 v237, v237, s0
	v_lshl_add_u64 v[26:27], s[98:99], 0, v[170:171]
	global_store_short v[26:27], v237, off
	v_add_f32_e32 v236, v250, v224
	v_cvt_pk_bf16_f32 v236, v236, s0
	v_lshl_add_u64 v[24:25], s[98:99], 0, v[172:173]
	global_store_short v[24:25], v236, off
	v_add_f32_e32 v237, v251, v225
	v_cvt_pk_bf16_f32 v237, v237, s0
	v_lshl_add_u64 v[26:27], s[98:99], 0, v[174:175]
	global_store_short v[26:27], v237, off
	v_add_f32_e32 v236, v252, v226
	v_cvt_pk_bf16_f32 v236, v236, s0
	v_lshl_add_u64 v[24:25], s[98:99], 0, v[176:177]
	global_store_short v[24:25], v236, off
	v_add_f32_e32 v237, v253, v227
	v_cvt_pk_bf16_f32 v237, v237, s0
	v_lshl_add_u64 v[26:27], s[98:99], 0, v[178:179]
	global_store_short v[26:27], v237, off
	v_add_f32_e32 v236, v254, v228
	v_cvt_pk_bf16_f32 v236, v236, s0
	v_lshl_add_u64 v[24:25], s[98:99], 0, v[180:181]
	global_store_short v[24:25], v236, off
	v_add_f32_e32 v237, v255, v229
	v_cvt_pk_bf16_f32 v237, v237, s0
	v_lshl_add_u64 v[26:27], s[98:99], 0, v[182:183]
	global_store_short v[26:27], v237, off
.Lss1_skip:
	s_mov_b64 exec, -1
	s_cbranch_scc1 .LBB0_489
	v_add_co_u32_e32 v18, vcc, 0x8050000, v196
	v_lshl_add_u64 v[16:17], v[196:197], 0, s[28:29]
	s_nop 0
	v_addc_co_u32_e32 v19, vcc, 0, v197, vcc
	global_load_dwordx4 v[68:71], v[18:19], off
	global_load_dwordx4 v[72:75], v[16:17], off offset:16
	v_add_co_u32_e32 v18, vcc, 0xc014000, v192
	v_lshl_add_u64 v[16:17], v[192:193], 0, s[30:31]
	s_nop 0
	v_addc_co_u32_e32 v19, vcc, 0, v193, vcc
	global_load_dwordx4 v[76:79], v[18:19], off
	global_load_dwordx4 v[80:83], v[16:17], off offset:16
	v_add_co_u32_e32 v16, vcc, 0x680a000, v194
	s_nop 1
	v_addc_co_u32_e32 v17, vcc, 0, v195, vcc
	global_load_dwordx4 v[84:87], v[16:17], off
	s_and_saveexec_b64 s[52:53], s[0:1]
	s_cbranch_execz .LBB0_488
	v_lshl_add_u64 v[16:17], s[94:95], 0, v[190:191]
	global_load_dword v198, v[16:17], off offset:-512

.Lsw1_join:
	ds_write_b16 v144, v136 offset:62464
	ds_write_b16_d16_hi v144, v136 offset:62608
	ds_write_b16 v144, v137 offset:62752
	ds_write_b16_d16_hi v144, v137 offset:62896
	ds_write_b16 v144, v138 offset:63040
	ds_write_b16_d16_hi v144, v138 offset:63184
	ds_write_b16 v144, v139 offset:63328
	ds_write_b16_d16_hi v144, v139 offset:63472
	s_and_saveexec_b64 s[52:53], s[0:1]
	ds_write_b32 v205, v201
	s_or_b64 exec, exec, s[52:53]
	s_waitcnt lgkmcnt(0)
	s_barrier
	s_and_saveexec_b64 s[52:53], s[4:5]
	s_cbranch_execz .Lss2_hi
	ds_read_b128 v[214:217], v206 offset:17408
	ds_read_b128 v[218:221], v207
	ds_read_b128 v[222:225], v206 offset:17440
	ds_read_b128 v[226:229], v207 offset:32
	ds_read_b128 v[240:243], v206 offset:17472
	ds_read_b128 v[244:247], v207 offset:64
	ds_read_b128 v[248:251], v206 offset:17504
	ds_read_b128 v[252:255], v207 offset:96
	s_waitcnt lgkmcnt(6)
	v_mfma_f32_32x32x16_bf16 v[32:47], v[214:217], v[218:221], 0
	ds_read_b128 v[214:217], v206 offset:17536
	ds_read_b128 v[218:221], v207 offset:128
	s_waitcnt lgkmcnt(6)
	v_mfma_f32_32x32x16_bf16 v[32:47], v[222:225], v[226:229], v[32:47]
	ds_read_b128 v[222:225], v206 offset:17568
	ds_read_b128 v[226:229], v207 offset:160
	s_waitcnt lgkmcnt(6)
	v_mfma_f32_32x32x16_bf16 v[32:47], v[240:243], v[244:247], v[32:47]
	ds_read_b128 v[240:243], v206 offset:17600
	ds_read_b128 v[244:247], v207 offset:192
	s_waitcnt lgkmcnt(6)
	v_mfma_f32_32x32x16_bf16 v[32:47], v[248:251], v[252:255], v[32:47]
	ds_read_b128 v[248:251], v206 offset:17632
	ds_read_b128 v[252:255], v207 offset:224
	s_waitcnt lgkmcnt(6)
	v_mfma_f32_32x32x16_bf16 v[32:47], v[214:217], v[218:221], v[32:47]
	s_waitcnt lgkmcnt(4)
	v_mfma_f32_32x32x16_bf16 v[32:47], v[222:225], v[226:229], v[32:47]
	s_waitcnt lgkmcnt(2)
	v_mfma_f32_32x32x16_bf16 v[32:47], v[240:243], v[244:247], v[32:47]
	s_waitcnt lgkmcnt(0)
	v_mfma_f32_32x32x16_bf16 v[32:47], v[248:251], v[252:255], v[32:47]
	v_and_b32_e32 v236, 0xff, v208
	v_lshlrev_b32_e32 v236, 4, v236
	v_add_u32_e32 v236, 0x18000, v236
	s_nop 11
	ds_write_b128 v236, v[32:35]
	ds_write_b128 v236, v[36:39] offset:4096
	ds_write_b128 v236, v[40:43] offset:8192
	ds_write_b128 v236, v[44:47] offset:12288
	s_branch .LBB0_493
.Lss2_hi:
	s_mov_b64 exec, s[52:53]
	s_add_i32 s10, s85, 0xfffffec0
	s_add_i32 s87, s86, 0x140
	s_and_b64 s[96:97], s[48:49], exec
	s_cselect_b32 s10, s10, s87
	s_add_u32 s96, s46, s10
	s_addc_u32 s97, 0, s47
	s_lshl_b64 s[98:99], s[96:97], 11
	ds_read_b128 v[214:217], v209 offset:53248
	ds_read_b128 v[218:221], v210 offset:62464
	ds_read_b128 v[222:225], v209 offset:53280
	ds_read_b128 v[226:229], v210 offset:62496
	ds_read_b128 v[16:19], v209 offset:53312
	ds_read_b128 v[20:23], v210 offset:62528
	ds_read_b128 v[24:27], v209 offset:53344
	ds_read_b128 v[28:31], v210 offset:62560
	s_waitcnt lgkmcnt(6)
	v_mfma_f32_32x32x16_bf16 v[240:255], v[214:217], v[218:221], 0
	s_waitcnt lgkmcnt(4)
	v_mfma_f32_32x32x16_bf16 v[240:255], v[222:225], v[226:229], v[240:255]
	s_waitcnt lgkmcnt(2)
	v_mfma_f32_32x32x16_bf16 v[240:255], v[16:19], v[20:23], v[240:255]
	s_waitcnt lgkmcnt(0)
	v_mfma_f32_32x32x16_bf16 v[240:255], v[24:27], v[28:31], v[240:255]
.LBB0_493:
	s_or_b64 exec, exec, s[52:53]
	ds_read_b128 v[16:19], v212 offset:96
	ds_read_b128 v[20:23], v212 offset:64
	ds_read_b128 v[24:27], v212 offset:32
	ds_read_b128 v[28:31], v212
	ds_read_b128 v[32:35], v211 offset:34816
	s_waitcnt lgkmcnt(4)
	v_pk_mul_f32 v[12:13], v[12:13], v[16:17]
	v_pk_mul_f32 v[14:15], v[14:15], v[18:19]
	ds_read_b128 v[16:19], v210 offset:62464
	s_waitcnt lgkmcnt(4)
	v_pk_mul_f32 v[8:9], v[8:9], v[20:21]
	s_waitcnt lgkmcnt(3)
	v_pk_mul_f32 v[4:5], v[4:5], v[24:25]
	v_pk_mul_f32 v[10:11], v[10:11], v[22:23]
	v_pk_mul_f32 v[6:7], v[6:7], v[26:27]
	s_waitcnt lgkmcnt(2)
	v_pk_mul_f32 v[2:3], v[2:3], v[30:31]
	v_pk_mul_f32 v[0:1], v[0:1], v[28:29]
	ds_read_b128 v[20:23], v211 offset:34848
	ds_read_b128 v[24:27], v210 offset:62496
	s_waitcnt lgkmcnt(2)
	v_mfma_f32_32x32x16_bf16 v[0:15], v[32:35], v[16:19], v[0:15]
	s_cmp_gt_u32 s84, 57
	s_waitcnt lgkmcnt(0)
	v_mfma_f32_32x32x16_bf16 v[0:15], v[20:23], v[24:27], v[0:15]
	ds_read_b128 v[16:19], v211 offset:34880
	ds_read_b128 v[20:23], v210 offset:62528
	ds_read_b128 v[24:27], v211 offset:34912
	ds_read_b128 v[28:31], v210 offset:62560
	s_waitcnt lgkmcnt(0)
	s_barrier
	s_waitcnt lgkmcnt(2)
	v_mfma_f32_32x32x16_bf16 v[0:15], v[16:19], v[20:23], v[0:15]
	s_waitcnt lgkmcnt(0)
	v_mfma_f32_32x32x16_bf16 v[0:15], v[24:27], v[28:31], v[0:15]
	s_nop 11
	v_cvt_pk_bf16_f32 v16, v0, v1
	v_cvt_pk_bf16_f32 v17, v2, v3
	v_cvt_pk_bf16_f32 v18, v4, v5
	v_cvt_pk_bf16_f32 v19, v6, v7
	v_cvt_pk_bf16_f32 v20, v8, v9
	v_cvt_pk_bf16_f32 v21, v10, v11
	v_cvt_pk_bf16_f32 v22, v12, v13
	v_cvt_pk_bf16_f32 v23, v14, v15
	ds_write2_b64 v213, v[16:17], v[18:19] offset1:2
	ds_write2_b64 v213, v[20:21], v[22:23] offset0:4 offset1:6
	v_lshrrev_b32_e32 v236, 8, v208
	v_cmpx_ne_u32_e64 s[100:101], 0, v236
	s_cbranch_execz .Lss2_skip
	v_and_b32_e32 v236, 0xff, v208
	v_lshlrev_b32_e32 v236, 4, v236
	v_add_u32_e32 v236, 0x18000, v236
	ds_read_b128 v[214:217], v236
	ds_read_b128 v[218:221], v236 offset:4096
	ds_read_b128 v[222:225], v236 offset:8192
	ds_read_b128 v[226:229], v236 offset:12288
	s_waitcnt lgkmcnt(0)
	v_add_f32_e32 v236, v240, v214
	v_cvt_pk_bf16_f32 v236, v236, s0
	v_lshl_add_u64 v[24:25], s[98:99], 0, v[152:153]
	global_store_short v[24:25], v236, off
	v_add_f32_e32 v237, v241, v215
	v_cvt_pk_bf16_f32 v237, v237, s0
	v_lshl_add_u64 v[26:27], s[98:99], 0, v[154:155]
	global_store_short v[26:27], v237, off
	v_add_f32_e32 v236, v242, v216
	v_cvt_pk_bf16_f32 v236, v236, s0
	v_lshl_add_u64 v[24:25], s[98:99], 0, v[156:157]
	global_store_short v[24:25], v236, off
	v_add_f32_e32 v237, v243, v217
	v_cvt_pk_bf16_f32 v237, v237, s0
	v_lshl_add_u64 v[26:27], s[98:99], 0, v[158:159]
	global_store_short v[26:27], v237, off
	v_add_f32_e32 v236, v244, v218
	v_cvt_pk_bf16_f32 v236, v236, s0
	v_lshl_add_u64 v[24:25], s[98:99], 0, v[160:161]
	global_store_short v[24:25], v236, off
	v_add_f32_e32 v237, v245, v219
	v_cvt_pk_bf16_f32 v237, v237, s0
	v_lshl_add_u64 v[26:27], s[98:99], 0, v[162:163]
	global_store_short v[26:27], v237, off
	v_add_f32_e32 v236, v246, v220
	v_cvt_pk_bf16_f32 v236, v236, s0
	v_lshl_add_u64 v[24:25], s[98:99], 0, v[164:165]
	global_store_short v[24:25], v236, off
	v_add_f32_e32 v237, v247, v221
	v_cvt_pk_bf16_f32 v237, v237, s0
	v_lshl_add_u64 v[26:27], s[98:99], 0, v[166:167]
	global_store_short v[26:27], v237, off
	v_add_f32_e32 v236, v248, v222
	v_cvt_pk_bf16_f32 v236, v236, s0
	v_lshl_add_u64 v[24:25], s[98:99], 0, v[168:169]
	global_store_short v[24:25], v236, off
	v_add_f32_e32 v237, v249, v223
	v_cvt_pk_bf16_f32 v237, v237, s0
	v_lshl_add_u64 v[26:27], s[98:99], 0, v[170:171]
	global_store_short v[26:27], v237, off
	v_add_f32_e32 v236, v250, v224
	v_cvt_pk_bf16_f32 v236, v236, s0
	v_lshl_add_u64 v[24:25], s[98:99], 0, v[172:173]
	global_store_short v[24:25], v236, off
	v_add_f32_e32 v237, v251, v225
	v_cvt_pk_bf16_f32 v237, v237, s0
	v_lshl_add_u64 v[26:27], s[98:99], 0, v[174:175]
	global_store_short v[26:27], v237, off
	v_add_f32_e32 v236, v252, v226
	v_cvt_pk_bf16_f32 v236, v236, s0
	v_lshl_add_u64 v[24:25], s[98:99], 0, v[176:177]
	global_store_short v[24:25], v236, off
	v_add_f32_e32 v237, v253, v227
	v_cvt_pk_bf16_f32 v237, v237, s0
	v_lshl_add_u64 v[26:27], s[98:99], 0, v[178:179]
	global_store_short v[26:27], v237, off
	v_add_f32_e32 v236, v254, v228
	v_cvt_pk_bf16_f32 v236, v236, s0
	v_lshl_add_u64 v[24:25], s[98:99], 0, v[180:181]
	global_store_short v[24:25], v236, off
	v_add_f32_e32 v237, v255, v229
	v_cvt_pk_bf16_f32 v237, v237, s0
	v_lshl_add_u64 v[26:27], s[98:99], 0, v[182:183]
	global_store_short v[26:27], v237, off
.Lss2_skip:
	s_mov_b64 exec, -1
	s_cbranch_scc1 .LBB0_497
	v_add_co_u32_e32 v18, vcc, 0x8060000, v196
	v_lshl_add_u64 v[16:17], v[196:197], 0, s[34:35]
	s_nop 0
	v_addc_co_u32_e32 v19, vcc, 0, v197, vcc
	global_load_dwordx4 v[88:91], v[18:19], off
	global_load_dwordx4 v[92:95], v[16:17], off offset:16
	v_add_co_u32_e32 v18, vcc, 0xc018000, v192
	v_lshl_add_u64 v[16:17], v[192:193], 0, s[36:37]
	s_nop 0
	v_addc_co_u32_e32 v19, vcc, 0, v193, vcc
	global_load_dwordx4 v[100:103], v[18:19], off
	global_load_dwordx4 v[104:107], v[16:17], off offset:16
	v_add_co_u32_e32 v16, vcc, 0x680c000, v194
	s_nop 1
	v_addc_co_u32_e32 v17, vcc, 0, v195, vcc
	global_load_dwordx4 v[108:111], v[16:17], off
	s_and_saveexec_b64 s[52:53], s[0:1]
	s_cbranch_execz .LBB0_496
	v_lshl_add_u64 v[16:17], s[94:95], 0, v[190:191]
	global_load_dword v201, v[16:17], off

.Lsw2_join:
	ds_write_b16 v144, v140 offset:62464
	ds_write_b16_d16_hi v144, v140 offset:62608
	ds_write_b16 v144, v141 offset:62752
	ds_write_b16_d16_hi v144, v141 offset:62896
	ds_write_b16 v144, v142 offset:63040
	ds_write_b16_d16_hi v144, v142 offset:63184
	ds_write_b16 v144, v143 offset:63328
	ds_write_b16_d16_hi v144, v143 offset:63472
	s_and_saveexec_b64 s[52:53], s[0:1]
	ds_write_b32 v205, v200
	s_or_b64 exec, exec, s[52:53]
	s_waitcnt lgkmcnt(0)
	s_barrier
	s_and_saveexec_b64 s[52:53], s[4:5]
	s_cbranch_execz .Lss3_hi
	ds_read_b128 v[214:217], v206 offset:17408
	ds_read_b128 v[218:221], v207
	ds_read_b128 v[222:225], v206 offset:17440
	ds_read_b128 v[226:229], v207 offset:32
	ds_read_b128 v[240:243], v206 offset:17472
	ds_read_b128 v[244:247], v207 offset:64
	ds_read_b128 v[248:251], v206 offset:17504
	ds_read_b128 v[252:255], v207 offset:96
	s_waitcnt lgkmcnt(6)
	v_mfma_f32_32x32x16_bf16 v[32:47], v[214:217], v[218:221], 0
	ds_read_b128 v[214:217], v206 offset:17536
	ds_read_b128 v[218:221], v207 offset:128
	s_waitcnt lgkmcnt(6)
	v_mfma_f32_32x32x16_bf16 v[32:47], v[222:225], v[226:229], v[32:47]
	ds_read_b128 v[222:225], v206 offset:17568
	ds_read_b128 v[226:229], v207 offset:160
	s_waitcnt lgkmcnt(6)
	v_mfma_f32_32x32x16_bf16 v[32:47], v[240:243], v[244:247], v[32:47]
	ds_read_b128 v[240:243], v206 offset:17600
	ds_read_b128 v[244:247], v207 offset:192
	s_waitcnt lgkmcnt(6)
	v_mfma_f32_32x32x16_bf16 v[32:47], v[248:251], v[252:255], v[32:47]
	ds_read_b128 v[248:251], v206 offset:17632
	ds_read_b128 v[252:255], v207 offset:224
	s_waitcnt lgkmcnt(6)
	v_mfma_f32_32x32x16_bf16 v[32:47], v[214:217], v[218:221], v[32:47]
	s_waitcnt lgkmcnt(4)
	v_mfma_f32_32x32x16_bf16 v[32:47], v[222:225], v[226:229], v[32:47]
	s_waitcnt lgkmcnt(2)
	v_mfma_f32_32x32x16_bf16 v[32:47], v[240:243], v[244:247], v[32:47]
	s_waitcnt lgkmcnt(0)
	v_mfma_f32_32x32x16_bf16 v[32:47], v[248:251], v[252:255], v[32:47]
	v_and_b32_e32 v236, 0xff, v208
	v_lshlrev_b32_e32 v236, 4, v236
	v_add_u32_e32 v236, 0x18000, v236
	s_nop 11
	ds_write_b128 v236, v[32:35]
	ds_write_b128 v236, v[36:39] offset:4096
	ds_write_b128 v236, v[40:43] offset:8192
	ds_write_b128 v236, v[44:47] offset:12288
	s_branch .LBB0_501
.Lss3_hi:
	s_mov_b64 exec, s[52:53]
	s_add_i32 s10, s85, 0xffffff00
	s_add_i32 s87, s86, 0x100
	s_and_b64 s[96:97], s[48:49], exec
	s_cselect_b32 s10, s10, s87
	s_add_u32 s96, s46, s10
	s_addc_u32 s97, 0, s47
	s_lshl_b64 s[98:99], s[96:97], 11
	ds_read_b128 v[214:217], v209 offset:53248
	ds_read_b128 v[218:221], v210 offset:62464
	ds_read_b128 v[222:225], v209 offset:53280
	ds_read_b128 v[226:229], v210 offset:62496
	ds_read_b128 v[16:19], v209 offset:53312
	ds_read_b128 v[20:23], v210 offset:62528
	ds_read_b128 v[24:27], v209 offset:53344
	ds_read_b128 v[28:31], v210 offset:62560
	s_waitcnt lgkmcnt(6)
	v_mfma_f32_32x32x16_bf16 v[240:255], v[214:217], v[218:221], 0
	s_waitcnt lgkmcnt(4)
	v_mfma_f32_32x32x16_bf16 v[240:255], v[222:225], v[226:229], v[240:255]
	s_waitcnt lgkmcnt(2)
	v_mfma_f32_32x32x16_bf16 v[240:255], v[16:19], v[20:23], v[240:255]
	s_waitcnt lgkmcnt(0)
	v_mfma_f32_32x32x16_bf16 v[240:255], v[24:27], v[28:31], v[240:255]
.LBB0_501:
	s_or_b64 exec, exec, s[52:53]
	ds_read_b128 v[16:19], v212 offset:96
	ds_read_b128 v[20:23], v212 offset:64
	ds_read_b128 v[24:27], v212 offset:32
	ds_read_b128 v[28:31], v212
	ds_read_b128 v[32:35], v211 offset:34816
	s_waitcnt lgkmcnt(4)
	v_pk_mul_f32 v[12:13], v[12:13], v[16:17]
	v_pk_mul_f32 v[14:15], v[14:15], v[18:19]
	ds_read_b128 v[16:19], v210 offset:62464
	s_waitcnt lgkmcnt(4)
	v_pk_mul_f32 v[8:9], v[8:9], v[20:21]
	s_waitcnt lgkmcnt(3)
	v_pk_mul_f32 v[4:5], v[4:5], v[24:25]
	v_pk_mul_f32 v[10:11], v[10:11], v[22:23]
	v_pk_mul_f32 v[6:7], v[6:7], v[26:27]
	s_waitcnt lgkmcnt(2)
	v_pk_mul_f32 v[2:3], v[2:3], v[30:31]
	v_pk_mul_f32 v[0:1], v[0:1], v[28:29]
	ds_read_b128 v[20:23], v211 offset:34848
	ds_read_b128 v[24:27], v210 offset:62496
	s_waitcnt lgkmcnt(2)
	v_mfma_f32_32x32x16_bf16 v[0:15], v[32:35], v[16:19], v[0:15]
	s_cmp_gt_u32 s84, 56
	s_waitcnt lgkmcnt(0)
	v_mfma_f32_32x32x16_bf16 v[0:15], v[20:23], v[24:27], v[0:15]
	ds_read_b128 v[16:19], v211 offset:34880
	ds_read_b128 v[20:23], v210 offset:62528
	ds_read_b128 v[24:27], v211 offset:34912
	ds_read_b128 v[28:31], v210 offset:62560
	s_waitcnt lgkmcnt(0)
	s_barrier
	s_waitcnt lgkmcnt(2)
	v_mfma_f32_32x32x16_bf16 v[0:15], v[16:19], v[20:23], v[0:15]
	s_waitcnt lgkmcnt(0)
	v_mfma_f32_32x32x16_bf16 v[0:15], v[24:27], v[28:31], v[0:15]
	s_nop 11
	v_cvt_pk_bf16_f32 v16, v0, v1
	v_cvt_pk_bf16_f32 v17, v2, v3
	v_cvt_pk_bf16_f32 v18, v4, v5
	v_cvt_pk_bf16_f32 v19, v6, v7
	v_cvt_pk_bf16_f32 v20, v8, v9
	v_cvt_pk_bf16_f32 v21, v10, v11
	v_cvt_pk_bf16_f32 v22, v12, v13
	v_cvt_pk_bf16_f32 v23, v14, v15
	ds_write2_b64 v213, v[16:17], v[18:19] offset1:2
	ds_write2_b64 v213, v[20:21], v[22:23] offset0:4 offset1:6
	v_lshrrev_b32_e32 v236, 8, v208
	v_cmpx_ne_u32_e64 s[100:101], 0, v236
	s_cbranch_execz .Lss3_skip
	v_and_b32_e32 v236, 0xff, v208
	v_lshlrev_b32_e32 v236, 4, v236
	v_add_u32_e32 v236, 0x18000, v236
	ds_read_b128 v[214:217], v236
	ds_read_b128 v[218:221], v236 offset:4096
	ds_read_b128 v[222:225], v236 offset:8192
	ds_read_b128 v[226:229], v236 offset:12288
	s_waitcnt lgkmcnt(0)
	v_add_f32_e32 v236, v240, v214
	v_cvt_pk_bf16_f32 v236, v236, s0
	v_lshl_add_u64 v[24:25], s[98:99], 0, v[152:153]
	global_store_short v[24:25], v236, off
	v_add_f32_e32 v237, v241, v215
	v_cvt_pk_bf16_f32 v237, v237, s0
	v_lshl_add_u64 v[26:27], s[98:99], 0, v[154:155]
	global_store_short v[26:27], v237, off
	v_add_f32_e32 v236, v242, v216
	v_cvt_pk_bf16_f32 v236, v236, s0
	v_lshl_add_u64 v[24:25], s[98:99], 0, v[156:157]
	global_store_short v[24:25], v236, off
	v_add_f32_e32 v237, v243, v217
	v_cvt_pk_bf16_f32 v237, v237, s0
	v_lshl_add_u64 v[26:27], s[98:99], 0, v[158:159]
	global_store_short v[26:27], v237, off
	v_add_f32_e32 v236, v244, v218
	v_cvt_pk_bf16_f32 v236, v236, s0
	v_lshl_add_u64 v[24:25], s[98:99], 0, v[160:161]
	global_store_short v[24:25], v236, off
	v_add_f32_e32 v237, v245, v219
	v_cvt_pk_bf16_f32 v237, v237, s0
	v_lshl_add_u64 v[26:27], s[98:99], 0, v[162:163]
	global_store_short v[26:27], v237, off
	v_add_f32_e32 v236, v246, v220
	v_cvt_pk_bf16_f32 v236, v236, s0
	v_lshl_add_u64 v[24:25], s[98:99], 0, v[164:165]
	global_store_short v[24:25], v236, off
	v_add_f32_e32 v237, v247, v221
	v_cvt_pk_bf16_f32 v237, v237, s0
	v_lshl_add_u64 v[26:27], s[98:99], 0, v[166:167]
	global_store_short v[26:27], v237, off
	v_add_f32_e32 v236, v248, v222
	v_cvt_pk_bf16_f32 v236, v236, s0
	v_lshl_add_u64 v[24:25], s[98:99], 0, v[168:169]
	global_store_short v[24:25], v236, off
	v_add_f32_e32 v237, v249, v223
	v_cvt_pk_bf16_f32 v237, v237, s0
	v_lshl_add_u64 v[26:27], s[98:99], 0, v[170:171]
	global_store_short v[26:27], v237, off
	v_add_f32_e32 v236, v250, v224
	v_cvt_pk_bf16_f32 v236, v236, s0
	v_lshl_add_u64 v[24:25], s[98:99], 0, v[172:173]
	global_store_short v[24:25], v236, off
	v_add_f32_e32 v237, v251, v225
	v_cvt_pk_bf16_f32 v237, v237, s0
	v_lshl_add_u64 v[26:27], s[98:99], 0, v[174:175]
	global_store_short v[26:27], v237, off
	v_add_f32_e32 v236, v252, v226
	v_cvt_pk_bf16_f32 v236, v236, s0
	v_lshl_add_u64 v[24:25], s[98:99], 0, v[176:177]
	global_store_short v[24:25], v236, off
	v_add_f32_e32 v237, v253, v227
	v_cvt_pk_bf16_f32 v237, v237, s0
	v_lshl_add_u64 v[26:27], s[98:99], 0, v[178:179]
	global_store_short v[26:27], v237, off
	v_add_f32_e32 v236, v254, v228
	v_cvt_pk_bf16_f32 v236, v236, s0
	v_lshl_add_u64 v[24:25], s[98:99], 0, v[180:181]
	global_store_short v[24:25], v236, off
	v_add_f32_e32 v237, v255, v229
	v_cvt_pk_bf16_f32 v237, v237, s0
	v_lshl_add_u64 v[26:27], s[98:99], 0, v[182:183]
	global_store_short v[26:27], v237, off
.Lss3_skip:
	s_mov_b64 exec, -1
	s_cbranch_scc1 .LBB0_472
	v_add_co_u32_e32 v18, vcc, 0x8070000, v196
	v_lshl_add_u64 v[16:17], v[196:197], 0, s[38:39]
	s_nop 0
	v_addc_co_u32_e32 v19, vcc, 0, v197, vcc
	global_load_dwordx4 v[112:115], v[18:19], off
	global_load_dwordx4 v[116:119], v[16:17], off offset:16
	v_add_co_u32_e32 v18, vcc, 0xc01c000, v192
	v_lshl_add_u64 v[16:17], v[192:193], 0, s[40:41]
	s_nop 0
	v_addc_co_u32_e32 v19, vcc, 0, v193, vcc
	global_load_dwordx4 v[124:127], v[18:19], off
	global_load_dwordx4 v[128:131], v[16:17], off offset:16
	v_add_co_u32_e32 v16, vcc, 0x680e000, v194
	s_nop 1
	v_addc_co_u32_e32 v17, vcc, 0, v195, vcc
	global_load_dwordx4 v[132:135], v[16:17], off
	s_and_saveexec_b64 s[52:53], s[0:1]
	s_cbranch_execz .LBB0_471
	v_lshl_add_u64 v[16:17], s[94:95], 0, v[190:191]
	global_load_dword v200, v[16:17], off offset:512
	s_branch .LBB0_471

.Lss4_hi:
	s_mov_b64 exec, s[50:51]
	s_add_i32 s10, s79, 0xfffffe40
	s_add_i32 s81, s80, 0x1c0
	s_and_b64 s[52:53], s[48:49], exec
	s_cselect_b32 s10, s10, s81
	s_add_u32 s52, s46, s10
	s_addc_u32 s53, 0, s47
	s_lshl_b64 s[98:99], s[52:53], 11
	ds_read_b128 v[214:217], v209 offset:53248
	ds_read_b128 v[218:221], v210 offset:62464
	ds_read_b128 v[222:225], v209 offset:53280
	ds_read_b128 v[226:229], v210 offset:62496
	ds_read_b128 v[16:19], v209 offset:53312
	ds_read_b128 v[20:23], v210 offset:62528
	ds_read_b128 v[24:27], v209 offset:53344
	ds_read_b128 v[28:31], v210 offset:62560
	s_waitcnt lgkmcnt(6)
	v_mfma_f32_32x32x16_bf16 v[240:255], v[214:217], v[218:221], 0
	s_waitcnt lgkmcnt(4)
	v_mfma_f32_32x32x16_bf16 v[240:255], v[222:225], v[226:229], v[240:255]
	s_waitcnt lgkmcnt(2)
	v_mfma_f32_32x32x16_bf16 v[240:255], v[16:19], v[20:23], v[240:255]
	s_waitcnt lgkmcnt(0)
	v_mfma_f32_32x32x16_bf16 v[240:255], v[24:27], v[28:31], v[240:255]
.LBB0_870:
	s_or_b64 exec, exec, s[50:51]
	ds_read_b128 v[16:19], v212 offset:96
	ds_read_b128 v[20:23], v212 offset:64
	ds_read_b128 v[24:27], v212 offset:32
	ds_read_b128 v[28:31], v212
	ds_read_b128 v[32:35], v211 offset:34816
	s_waitcnt lgkmcnt(4)
	v_pk_mul_f32 v[12:13], v[12:13], v[16:17]
	v_pk_mul_f32 v[14:15], v[14:15], v[18:19]
	ds_read_b128 v[16:19], v210 offset:62464
	s_waitcnt lgkmcnt(4)
	v_pk_mul_f32 v[8:9], v[8:9], v[20:21]
	s_waitcnt lgkmcnt(3)
	v_pk_mul_f32 v[4:5], v[4:5], v[24:25]
	s_waitcnt lgkmcnt(2)
	v_pk_mul_f32 v[0:1], v[0:1], v[28:29]
	v_pk_mul_f32 v[10:11], v[10:11], v[22:23]
	v_pk_mul_f32 v[6:7], v[6:7], v[26:27]
	v_pk_mul_f32 v[2:3], v[2:3], v[30:31]
	ds_read_b128 v[20:23], v211 offset:34848
	ds_read_b128 v[24:27], v210 offset:62496
	s_waitcnt lgkmcnt(2)
	v_mfma_f32_32x32x16_bf16 v[0:15], v[32:35], v[16:19], v[0:15]
	s_add_i32 s78, s78, 4
	s_cmp_gt_u32 s78, 59
	s_cselect_b64 s[50:51], -1, 0
	v_lshl_add_u64 v[196:197], s[92:93], 0, v[188:189]
	v_lshl_add_u64 v[192:193], s[92:93], 0, v[186:187]
	s_and_b64 vcc, exec, s[50:51]
	v_lshl_add_u64 v[194:195], s[94:95], 0, v[184:185]
	s_waitcnt lgkmcnt(0)
	v_mfma_f32_32x32x16_bf16 v[0:15], v[20:23], v[24:27], v[0:15]
	ds_read_b128 v[16:19], v211 offset:34880
	ds_read_b128 v[20:23], v210 offset:62528
	ds_read_b128 v[24:27], v211 offset:34912
	ds_read_b128 v[28:31], v210 offset:62560
	s_waitcnt lgkmcnt(0)
	s_barrier
	s_waitcnt lgkmcnt(2)
	v_mfma_f32_32x32x16_bf16 v[0:15], v[16:19], v[20:23], v[0:15]
	s_waitcnt lgkmcnt(0)
	v_mfma_f32_32x32x16_bf16 v[0:15], v[24:27], v[28:31], v[0:15]
	s_nop 11
	v_cvt_pk_bf16_f32 v16, v0, v1
	v_cvt_pk_bf16_f32 v17, v2, v3
	v_cvt_pk_bf16_f32 v18, v4, v5
	v_cvt_pk_bf16_f32 v19, v6, v7
	v_cvt_pk_bf16_f32 v20, v8, v9
	v_cvt_pk_bf16_f32 v21, v10, v11
	v_cvt_pk_bf16_f32 v22, v12, v13
	v_cvt_pk_bf16_f32 v23, v14, v15
	ds_write2_b64 v213, v[16:17], v[18:19] offset1:2
	ds_write2_b64 v213, v[20:21], v[22:23] offset0:4 offset1:6
	v_lshrrev_b32_e32 v236, 8, v208
	v_cmpx_ne_u32_e64 s[100:101], 0, v236
	s_cbranch_execz .Lss4_skip
	v_and_b32_e32 v236, 0xff, v208
	v_lshlrev_b32_e32 v236, 4, v236
	v_add_u32_e32 v236, 0x18000, v236
	ds_read_b128 v[214:217], v236
	ds_read_b128 v[218:221], v236 offset:4096
	ds_read_b128 v[222:225], v236 offset:8192
	ds_read_b128 v[226:229], v236 offset:12288
	s_waitcnt lgkmcnt(0)
	v_add_f32_e32 v236, v240, v214
	v_cvt_pk_bf16_f32 v236, v236, s0
	v_lshl_add_u64 v[24:25], s[98:99], 0, v[152:153]
	global_store_short v[24:25], v236, off
	v_add_f32_e32 v237, v241, v215
	v_cvt_pk_bf16_f32 v237, v237, s0
	v_lshl_add_u64 v[26:27], s[98:99], 0, v[154:155]
	global_store_short v[26:27], v237, off
	v_add_f32_e32 v236, v242, v216
	v_cvt_pk_bf16_f32 v236, v236, s0
	v_lshl_add_u64 v[24:25], s[98:99], 0, v[156:157]
	global_store_short v[24:25], v236, off
	v_add_f32_e32 v237, v243, v217
	v_cvt_pk_bf16_f32 v237, v237, s0
	v_lshl_add_u64 v[26:27], s[98:99], 0, v[158:159]
	global_store_short v[26:27], v237, off
	v_add_f32_e32 v236, v244, v218
	v_cvt_pk_bf16_f32 v236, v236, s0
	v_lshl_add_u64 v[24:25], s[98:99], 0, v[160:161]
	global_store_short v[24:25], v236, off
	v_add_f32_e32 v237, v245, v219
	v_cvt_pk_bf16_f32 v237, v237, s0
	v_lshl_add_u64 v[26:27], s[98:99], 0, v[162:163]
	global_store_short v[26:27], v237, off
	v_add_f32_e32 v236, v246, v220
	v_cvt_pk_bf16_f32 v236, v236, s0
	v_lshl_add_u64 v[24:25], s[98:99], 0, v[164:165]
	global_store_short v[24:25], v236, off
	v_add_f32_e32 v237, v247, v221
	v_cvt_pk_bf16_f32 v237, v237, s0
	v_lshl_add_u64 v[26:27], s[98:99], 0, v[166:167]
	global_store_short v[26:27], v237, off
	v_add_f32_e32 v236, v248, v222
	v_cvt_pk_bf16_f32 v236, v236, s0
	v_lshl_add_u64 v[24:25], s[98:99], 0, v[168:169]
	global_store_short v[24:25], v236, off
	v_add_f32_e32 v237, v249, v223
	v_cvt_pk_bf16_f32 v237, v237, s0
	v_lshl_add_u64 v[26:27], s[98:99], 0, v[170:171]
	global_store_short v[26:27], v237, off
	v_add_f32_e32 v236, v250, v224
	v_cvt_pk_bf16_f32 v236, v236, s0
	v_lshl_add_u64 v[24:25], s[98:99], 0, v[172:173]
	global_store_short v[24:25], v236, off
	v_add_f32_e32 v237, v251, v225
	v_cvt_pk_bf16_f32 v237, v237, s0
	v_lshl_add_u64 v[26:27], s[98:99], 0, v[174:175]
	global_store_short v[26:27], v237, off
	v_add_f32_e32 v236, v252, v226
	v_cvt_pk_bf16_f32 v236, v236, s0
	v_lshl_add_u64 v[24:25], s[98:99], 0, v[176:177]
	global_store_short v[24:25], v236, off
	v_add_f32_e32 v237, v253, v227
	v_cvt_pk_bf16_f32 v237, v237, s0
	v_lshl_add_u64 v[26:27], s[98:99], 0, v[178:179]
	global_store_short v[26:27], v237, off
	v_add_f32_e32 v236, v254, v228
	v_cvt_pk_bf16_f32 v236, v236, s0
	v_lshl_add_u64 v[24:25], s[98:99], 0, v[180:181]
	global_store_short v[24:25], v236, off
	v_add_f32_e32 v237, v255, v229
	v_cvt_pk_bf16_f32 v237, v237, s0
	v_lshl_add_u64 v[26:27], s[98:99], 0, v[182:183]
	global_store_short v[26:27], v237, off

.Lss5_hi:
	s_mov_b64 exec, s[52:53]
	s_add_i32 s10, s79, 0xfffffe80
	s_add_i32 s81, s80, 0x180
	s_and_b64 s[84:85], s[48:49], exec
	s_cselect_b32 s10, s10, s81
	s_add_u32 s84, s46, s10
	s_addc_u32 s85, 0, s47
	s_lshl_b64 s[98:99], s[84:85], 11
	ds_read_b128 v[214:217], v209 offset:53248
	ds_read_b128 v[218:221], v210 offset:62464
	ds_read_b128 v[222:225], v209 offset:53280
	ds_read_b128 v[226:229], v210 offset:62496
	ds_read_b128 v[16:19], v209 offset:53312
	ds_read_b128 v[20:23], v210 offset:62528
	ds_read_b128 v[24:27], v209 offset:53344
	ds_read_b128 v[28:31], v210 offset:62560
	s_waitcnt lgkmcnt(6)
	v_mfma_f32_32x32x16_bf16 v[240:255], v[214:217], v[218:221], 0
	s_waitcnt lgkmcnt(4)
	v_mfma_f32_32x32x16_bf16 v[240:255], v[222:225], v[226:229], v[240:255]
	s_waitcnt lgkmcnt(2)
	v_mfma_f32_32x32x16_bf16 v[240:255], v[16:19], v[20:23], v[240:255]
	s_waitcnt lgkmcnt(0)
	v_mfma_f32_32x32x16_bf16 v[240:255], v[24:27], v[28:31], v[240:255]
.LBB0_878:
	s_or_b64 exec, exec, s[52:53]
	ds_read_b128 v[16:19], v212 offset:96
	ds_read_b128 v[20:23], v212 offset:64
	ds_read_b128 v[24:27], v212 offset:32
	ds_read_b128 v[28:31], v212
	ds_read_b128 v[32:35], v211 offset:34816
	s_waitcnt lgkmcnt(4)
	v_pk_mul_f32 v[12:13], v[12:13], v[16:17]
	v_pk_mul_f32 v[14:15], v[14:15], v[18:19]
	ds_read_b128 v[16:19], v210 offset:62464
	s_waitcnt lgkmcnt(4)
	v_pk_mul_f32 v[8:9], v[8:9], v[20:21]
	s_waitcnt lgkmcnt(3)
	v_pk_mul_f32 v[4:5], v[4:5], v[24:25]
	v_pk_mul_f32 v[10:11], v[10:11], v[22:23]
	v_pk_mul_f32 v[6:7], v[6:7], v[26:27]
	s_waitcnt lgkmcnt(2)
	v_pk_mul_f32 v[2:3], v[2:3], v[30:31]
	v_pk_mul_f32 v[0:1], v[0:1], v[28:29]
	ds_read_b128 v[20:23], v211 offset:34848
	ds_read_b128 v[24:27], v210 offset:62496
	s_waitcnt lgkmcnt(2)
	v_mfma_f32_32x32x16_bf16 v[0:15], v[32:35], v[16:19], v[0:15]
	s_cmp_gt_u32 s78, 58
	s_waitcnt lgkmcnt(0)
	v_mfma_f32_32x32x16_bf16 v[0:15], v[20:23], v[24:27], v[0:15]
	ds_read_b128 v[16:19], v211 offset:34880
	ds_read_b128 v[20:23], v210 offset:62528
	ds_read_b128 v[24:27], v211 offset:34912
	ds_read_b128 v[28:31], v210 offset:62560
	s_waitcnt lgkmcnt(0)
	s_barrier
	s_waitcnt lgkmcnt(2)
	v_mfma_f32_32x32x16_bf16 v[0:15], v[16:19], v[20:23], v[0:15]
	s_waitcnt lgkmcnt(0)
	v_mfma_f32_32x32x16_bf16 v[0:15], v[24:27], v[28:31], v[0:15]
	s_nop 11
	v_cvt_pk_bf16_f32 v16, v0, v1
	v_cvt_pk_bf16_f32 v17, v2, v3
	v_cvt_pk_bf16_f32 v18, v4, v5
	v_cvt_pk_bf16_f32 v19, v6, v7
	v_cvt_pk_bf16_f32 v20, v8, v9
	v_cvt_pk_bf16_f32 v21, v10, v11
	v_cvt_pk_bf16_f32 v22, v12, v13
	v_cvt_pk_bf16_f32 v23, v14, v15
	ds_write2_b64 v213, v[16:17], v[18:19] offset1:2
	ds_write2_b64 v213, v[20:21], v[22:23] offset0:4 offset1:6
	v_lshrrev_b32_e32 v236, 8, v208
	v_cmpx_ne_u32_e64 s[100:101], 0, v236
	s_cbranch_execz .Lss5_skip
	v_and_b32_e32 v236, 0xff, v208
	v_lshlrev_b32_e32 v236, 4, v236
	v_add_u32_e32 v236, 0x18000, v236
	ds_read_b128 v[214:217], v236
	ds_read_b128 v[218:221], v236 offset:4096
	ds_read_b128 v[222:225], v236 offset:8192
	ds_read_b128 v[226:229], v236 offset:12288
	s_waitcnt lgkmcnt(0)
	v_add_f32_e32 v236, v240, v214
	v_cvt_pk_bf16_f32 v236, v236, s0
	v_lshl_add_u64 v[24:25], s[98:99], 0, v[152:153]
	global_store_short v[24:25], v236, off
	v_add_f32_e32 v237, v241, v215
	v_cvt_pk_bf16_f32 v237, v237, s0
	v_lshl_add_u64 v[26:27], s[98:99], 0, v[154:155]
	global_store_short v[26:27], v237, off
	v_add_f32_e32 v236, v242, v216
	v_cvt_pk_bf16_f32 v236, v236, s0
	v_lshl_add_u64 v[24:25], s[98:99], 0, v[156:157]
	global_store_short v[24:25], v236, off
	v_add_f32_e32 v237, v243, v217
	v_cvt_pk_bf16_f32 v237, v237, s0
	v_lshl_add_u64 v[26:27], s[98:99], 0, v[158:159]
	global_store_short v[26:27], v237, off
	v_add_f32_e32 v236, v244, v218
	v_cvt_pk_bf16_f32 v236, v236, s0
	v_lshl_add_u64 v[24:25], s[98:99], 0, v[160:161]
	global_store_short v[24:25], v236, off
	v_add_f32_e32 v237, v245, v219
	v_cvt_pk_bf16_f32 v237, v237, s0
	v_lshl_add_u64 v[26:27], s[98:99], 0, v[162:163]
	global_store_short v[26:27], v237, off
	v_add_f32_e32 v236, v246, v220
	v_cvt_pk_bf16_f32 v236, v236, s0
	v_lshl_add_u64 v[24:25], s[98:99], 0, v[164:165]
	global_store_short v[24:25], v236, off
	v_add_f32_e32 v237, v247, v221
	v_cvt_pk_bf16_f32 v237, v237, s0
	v_lshl_add_u64 v[26:27], s[98:99], 0, v[166:167]
	global_store_short v[26:27], v237, off
	v_add_f32_e32 v236, v248, v222
	v_cvt_pk_bf16_f32 v236, v236, s0
	v_lshl_add_u64 v[24:25], s[98:99], 0, v[168:169]
	global_store_short v[24:25], v236, off
	v_add_f32_e32 v237, v249, v223
	v_cvt_pk_bf16_f32 v237, v237, s0
	v_lshl_add_u64 v[26:27], s[98:99], 0, v[170:171]
	global_store_short v[26:27], v237, off
	v_add_f32_e32 v236, v250, v224
	v_cvt_pk_bf16_f32 v236, v236, s0
	v_lshl_add_u64 v[24:25], s[98:99], 0, v[172:173]
	global_store_short v[24:25], v236, off
	v_add_f32_e32 v237, v251, v225
	v_cvt_pk_bf16_f32 v237, v237, s0
	v_lshl_add_u64 v[26:27], s[98:99], 0, v[174:175]
	global_store_short v[26:27], v237, off
	v_add_f32_e32 v236, v252, v226
	v_cvt_pk_bf16_f32 v236, v236, s0
	v_lshl_add_u64 v[24:25], s[98:99], 0, v[176:177]
	global_store_short v[24:25], v236, off
	v_add_f32_e32 v237, v253, v227
	v_cvt_pk_bf16_f32 v237, v237, s0
	v_lshl_add_u64 v[26:27], s[98:99], 0, v[178:179]
	global_store_short v[26:27], v237, off
	v_add_f32_e32 v236, v254, v228
	v_cvt_pk_bf16_f32 v236, v236, s0
	v_lshl_add_u64 v[24:25], s[98:99], 0, v[180:181]
	global_store_short v[24:25], v236, off
	v_add_f32_e32 v237, v255, v229
	v_cvt_pk_bf16_f32 v237, v237, s0
	v_lshl_add_u64 v[26:27], s[98:99], 0, v[182:183]
	global_store_short v[26:27], v237, off

.Lss6_hi:
	s_mov_b64 exec, s[52:53]
	s_add_i32 s10, s79, 0xfffffec0
	s_add_i32 s81, s80, 0x140
	s_and_b64 s[84:85], s[48:49], exec
	s_cselect_b32 s10, s10, s81
	s_add_u32 s84, s46, s10
	s_addc_u32 s85, 0, s47
	s_lshl_b64 s[98:99], s[84:85], 11
	ds_read_b128 v[214:217], v209 offset:53248
	ds_read_b128 v[218:221], v210 offset:62464
	ds_read_b128 v[222:225], v209 offset:53280
	ds_read_b128 v[226:229], v210 offset:62496
	ds_read_b128 v[16:19], v209 offset:53312
	ds_read_b128 v[20:23], v210 offset:62528
	ds_read_b128 v[24:27], v209 offset:53344
	ds_read_b128 v[28:31], v210 offset:62560
	s_waitcnt lgkmcnt(6)
	v_mfma_f32_32x32x16_bf16 v[240:255], v[214:217], v[218:221], 0
	s_waitcnt lgkmcnt(4)
	v_mfma_f32_32x32x16_bf16 v[240:255], v[222:225], v[226:229], v[240:255]
	s_waitcnt lgkmcnt(2)
	v_mfma_f32_32x32x16_bf16 v[240:255], v[16:19], v[20:23], v[240:255]
	s_waitcnt lgkmcnt(0)
	v_mfma_f32_32x32x16_bf16 v[240:255], v[24:27], v[28:31], v[240:255]
.LBB0_886:
	s_or_b64 exec, exec, s[52:53]
	ds_read_b128 v[16:19], v212 offset:96
	ds_read_b128 v[20:23], v212 offset:64
	ds_read_b128 v[24:27], v212 offset:32
	ds_read_b128 v[28:31], v212
	ds_read_b128 v[32:35], v211 offset:34816
	s_waitcnt lgkmcnt(4)
	v_pk_mul_f32 v[12:13], v[12:13], v[16:17]
	v_pk_mul_f32 v[14:15], v[14:15], v[18:19]
	ds_read_b128 v[16:19], v210 offset:62464
	s_waitcnt lgkmcnt(4)
	v_pk_mul_f32 v[8:9], v[8:9], v[20:21]
	s_waitcnt lgkmcnt(3)
	v_pk_mul_f32 v[4:5], v[4:5], v[24:25]
	v_pk_mul_f32 v[10:11], v[10:11], v[22:23]
	v_pk_mul_f32 v[6:7], v[6:7], v[26:27]
	s_waitcnt lgkmcnt(2)
	v_pk_mul_f32 v[2:3], v[2:3], v[30:31]
	v_pk_mul_f32 v[0:1], v[0:1], v[28:29]
	ds_read_b128 v[20:23], v211 offset:34848
	ds_read_b128 v[24:27], v210 offset:62496
	s_waitcnt lgkmcnt(2)
	v_mfma_f32_32x32x16_bf16 v[0:15], v[32:35], v[16:19], v[0:15]
	s_cmp_gt_u32 s78, 57
	s_waitcnt lgkmcnt(0)
	v_mfma_f32_32x32x16_bf16 v[0:15], v[20:23], v[24:27], v[0:15]
	ds_read_b128 v[16:19], v211 offset:34880
	ds_read_b128 v[20:23], v210 offset:62528
	ds_read_b128 v[24:27], v211 offset:34912
	ds_read_b128 v[28:31], v210 offset:62560
	s_waitcnt lgkmcnt(0)
	s_barrier
	s_waitcnt lgkmcnt(2)
	v_mfma_f32_32x32x16_bf16 v[0:15], v[16:19], v[20:23], v[0:15]
	s_waitcnt lgkmcnt(0)
	v_mfma_f32_32x32x16_bf16 v[0:15], v[24:27], v[28:31], v[0:15]
	s_nop 11
	v_cvt_pk_bf16_f32 v16, v0, v1
	v_cvt_pk_bf16_f32 v17, v2, v3
	v_cvt_pk_bf16_f32 v18, v4, v5
	v_cvt_pk_bf16_f32 v19, v6, v7
	v_cvt_pk_bf16_f32 v20, v8, v9
	v_cvt_pk_bf16_f32 v21, v10, v11
	v_cvt_pk_bf16_f32 v22, v12, v13
	v_cvt_pk_bf16_f32 v23, v14, v15
	ds_write2_b64 v213, v[16:17], v[18:19] offset1:2
	ds_write2_b64 v213, v[20:21], v[22:23] offset0:4 offset1:6
	v_lshrrev_b32_e32 v236, 8, v208
	v_cmpx_ne_u32_e64 s[100:101], 0, v236
	s_cbranch_execz .Lss6_skip
	v_and_b32_e32 v236, 0xff, v208
	v_lshlrev_b32_e32 v236, 4, v236
	v_add_u32_e32 v236, 0x18000, v236
	ds_read_b128 v[214:217], v236
	ds_read_b128 v[218:221], v236 offset:4096
	ds_read_b128 v[222:225], v236 offset:8192
	ds_read_b128 v[226:229], v236 offset:12288
	s_waitcnt lgkmcnt(0)
	v_add_f32_e32 v236, v240, v214
	v_cvt_pk_bf16_f32 v236, v236, s0
	v_lshl_add_u64 v[24:25], s[98:99], 0, v[152:153]
	global_store_short v[24:25], v236, off
	v_add_f32_e32 v237, v241, v215
	v_cvt_pk_bf16_f32 v237, v237, s0
	v_lshl_add_u64 v[26:27], s[98:99], 0, v[154:155]
	global_store_short v[26:27], v237, off
	v_add_f32_e32 v236, v242, v216
	v_cvt_pk_bf16_f32 v236, v236, s0
	v_lshl_add_u64 v[24:25], s[98:99], 0, v[156:157]
	global_store_short v[24:25], v236, off
	v_add_f32_e32 v237, v243, v217
	v_cvt_pk_bf16_f32 v237, v237, s0
	v_lshl_add_u64 v[26:27], s[98:99], 0, v[158:159]
	global_store_short v[26:27], v237, off
	v_add_f32_e32 v236, v244, v218
	v_cvt_pk_bf16_f32 v236, v236, s0
	v_lshl_add_u64 v[24:25], s[98:99], 0, v[160:161]
	global_store_short v[24:25], v236, off
	v_add_f32_e32 v237, v245, v219
	v_cvt_pk_bf16_f32 v237, v237, s0
	v_lshl_add_u64 v[26:27], s[98:99], 0, v[162:163]
	global_store_short v[26:27], v237, off
	v_add_f32_e32 v236, v246, v220
	v_cvt_pk_bf16_f32 v236, v236, s0
	v_lshl_add_u64 v[24:25], s[98:99], 0, v[164:165]
	global_store_short v[24:25], v236, off
	v_add_f32_e32 v237, v247, v221
	v_cvt_pk_bf16_f32 v237, v237, s0
	v_lshl_add_u64 v[26:27], s[98:99], 0, v[166:167]
	global_store_short v[26:27], v237, off
	v_add_f32_e32 v236, v248, v222
	v_cvt_pk_bf16_f32 v236, v236, s0
	v_lshl_add_u64 v[24:25], s[98:99], 0, v[168:169]
	global_store_short v[24:25], v236, off
	v_add_f32_e32 v237, v249, v223
	v_cvt_pk_bf16_f32 v237, v237, s0
	v_lshl_add_u64 v[26:27], s[98:99], 0, v[170:171]
	global_store_short v[26:27], v237, off
	v_add_f32_e32 v236, v250, v224
	v_cvt_pk_bf16_f32 v236, v236, s0
	v_lshl_add_u64 v[24:25], s[98:99], 0, v[172:173]
	global_store_short v[24:25], v236, off
	v_add_f32_e32 v237, v251, v225
	v_cvt_pk_bf16_f32 v237, v237, s0
	v_lshl_add_u64 v[26:27], s[98:99], 0, v[174:175]
	global_store_short v[26:27], v237, off
	v_add_f32_e32 v236, v252, v226
	v_cvt_pk_bf16_f32 v236, v236, s0
	v_lshl_add_u64 v[24:25], s[98:99], 0, v[176:177]
	global_store_short v[24:25], v236, off
	v_add_f32_e32 v237, v253, v227
	v_cvt_pk_bf16_f32 v237, v237, s0
	v_lshl_add_u64 v[26:27], s[98:99], 0, v[178:179]
	global_store_short v[26:27], v237, off
	v_add_f32_e32 v236, v254, v228
	v_cvt_pk_bf16_f32 v236, v236, s0
	v_lshl_add_u64 v[24:25], s[98:99], 0, v[180:181]
	global_store_short v[24:25], v236, off
	v_add_f32_e32 v237, v255, v229
	v_cvt_pk_bf16_f32 v237, v237, s0
	v_lshl_add_u64 v[26:27], s[98:99], 0, v[182:183]
	global_store_short v[26:27], v237, off

.Lss7_hi:
	s_mov_b64 exec, s[52:53]
	s_add_i32 s10, s79, 0xffffff00
	s_add_i32 s81, s80, 0x100
	s_and_b64 s[84:85], s[48:49], exec
	s_cselect_b32 s10, s10, s81
	s_add_u32 s84, s46, s10
	s_addc_u32 s85, 0, s47
	s_lshl_b64 s[98:99], s[84:85], 11
	ds_read_b128 v[214:217], v209 offset:53248
	ds_read_b128 v[218:221], v210 offset:62464
	ds_read_b128 v[222:225], v209 offset:53280
	ds_read_b128 v[226:229], v210 offset:62496
	ds_read_b128 v[16:19], v209 offset:53312
	ds_read_b128 v[20:23], v210 offset:62528
	ds_read_b128 v[24:27], v209 offset:53344
	ds_read_b128 v[28:31], v210 offset:62560
	s_waitcnt lgkmcnt(6)
	v_mfma_f32_32x32x16_bf16 v[240:255], v[214:217], v[218:221], 0
	s_waitcnt lgkmcnt(4)
	v_mfma_f32_32x32x16_bf16 v[240:255], v[222:225], v[226:229], v[240:255]
	s_waitcnt lgkmcnt(2)
	v_mfma_f32_32x32x16_bf16 v[240:255], v[16:19], v[20:23], v[240:255]
	s_waitcnt lgkmcnt(0)
	v_mfma_f32_32x32x16_bf16 v[240:255], v[24:27], v[28:31], v[240:255]
.LBB0_894:
	s_or_b64 exec, exec, s[52:53]
	ds_read_b128 v[16:19], v212 offset:96
	ds_read_b128 v[20:23], v212 offset:64
	ds_read_b128 v[24:27], v212 offset:32
	ds_read_b128 v[28:31], v212
	ds_read_b128 v[32:35], v211 offset:34816
	s_waitcnt lgkmcnt(4)
	v_pk_mul_f32 v[12:13], v[12:13], v[16:17]
	v_pk_mul_f32 v[14:15], v[14:15], v[18:19]
	ds_read_b128 v[16:19], v210 offset:62464
	s_waitcnt lgkmcnt(4)
	v_pk_mul_f32 v[8:9], v[8:9], v[20:21]
	s_waitcnt lgkmcnt(3)
	v_pk_mul_f32 v[4:5], v[4:5], v[24:25]
	v_pk_mul_f32 v[10:11], v[10:11], v[22:23]
	v_pk_mul_f32 v[6:7], v[6:7], v[26:27]
	s_waitcnt lgkmcnt(2)
	v_pk_mul_f32 v[2:3], v[2:3], v[30:31]
	v_pk_mul_f32 v[0:1], v[0:1], v[28:29]
	ds_read_b128 v[20:23], v211 offset:34848
	ds_read_b128 v[24:27], v210 offset:62496
	s_waitcnt lgkmcnt(2)
	v_mfma_f32_32x32x16_bf16 v[0:15], v[32:35], v[16:19], v[0:15]
	s_cmp_gt_u32 s78, 56
	s_waitcnt lgkmcnt(0)
	v_mfma_f32_32x32x16_bf16 v[0:15], v[20:23], v[24:27], v[0:15]
	ds_read_b128 v[16:19], v211 offset:34880
	ds_read_b128 v[20:23], v210 offset:62528
	ds_read_b128 v[24:27], v211 offset:34912
	ds_read_b128 v[28:31], v210 offset:62560
	s_waitcnt lgkmcnt(0)
	s_barrier
	s_waitcnt lgkmcnt(2)
	v_mfma_f32_32x32x16_bf16 v[0:15], v[16:19], v[20:23], v[0:15]
	s_waitcnt lgkmcnt(0)
	v_mfma_f32_32x32x16_bf16 v[0:15], v[24:27], v[28:31], v[0:15]
	s_nop 11
	v_cvt_pk_bf16_f32 v16, v0, v1
	v_cvt_pk_bf16_f32 v17, v2, v3
	v_cvt_pk_bf16_f32 v18, v4, v5
	v_cvt_pk_bf16_f32 v19, v6, v7
	v_cvt_pk_bf16_f32 v20, v8, v9
	v_cvt_pk_bf16_f32 v21, v10, v11
	v_cvt_pk_bf16_f32 v22, v12, v13
	v_cvt_pk_bf16_f32 v23, v14, v15
	ds_write2_b64 v213, v[16:17], v[18:19] offset1:2
	ds_write2_b64 v213, v[20:21], v[22:23] offset0:4 offset1:6
	v_lshrrev_b32_e32 v236, 8, v208
	v_cmpx_ne_u32_e64 s[100:101], 0, v236
	s_cbranch_execz .Lss7_skip
	v_and_b32_e32 v236, 0xff, v208
	v_lshlrev_b32_e32 v236, 4, v236
	v_add_u32_e32 v236, 0x18000, v236
	ds_read_b128 v[214:217], v236
	ds_read_b128 v[218:221], v236 offset:4096
	ds_read_b128 v[222:225], v236 offset:8192
	ds_read_b128 v[226:229], v236 offset:12288
	s_waitcnt lgkmcnt(0)
	v_add_f32_e32 v236, v240, v214
	v_cvt_pk_bf16_f32 v236, v236, s0
	v_lshl_add_u64 v[24:25], s[98:99], 0, v[152:153]
	global_store_short v[24:25], v236, off
	v_add_f32_e32 v237, v241, v215
	v_cvt_pk_bf16_f32 v237, v237, s0
	v_lshl_add_u64 v[26:27], s[98:99], 0, v[154:155]
	global_store_short v[26:27], v237, off
	v_add_f32_e32 v236, v242, v216
	v_cvt_pk_bf16_f32 v236, v236, s0
	v_lshl_add_u64 v[24:25], s[98:99], 0, v[156:157]
	global_store_short v[24:25], v236, off
	v_add_f32_e32 v237, v243, v217
	v_cvt_pk_bf16_f32 v237, v237, s0
	v_lshl_add_u64 v[26:27], s[98:99], 0, v[158:159]
	global_store_short v[26:27], v237, off
	v_add_f32_e32 v236, v244, v218
	v_cvt_pk_bf16_f32 v236, v236, s0
	v_lshl_add_u64 v[24:25], s[98:99], 0, v[160:161]
	global_store_short v[24:25], v236, off
	v_add_f32_e32 v237, v245, v219
	v_cvt_pk_bf16_f32 v237, v237, s0
	v_lshl_add_u64 v[26:27], s[98:99], 0, v[162:163]
	global_store_short v[26:27], v237, off
	v_add_f32_e32 v236, v246, v220
	v_cvt_pk_bf16_f32 v236, v236, s0
	v_lshl_add_u64 v[24:25], s[98:99], 0, v[164:165]
	global_store_short v[24:25], v236, off
	v_add_f32_e32 v237, v247, v221
	v_cvt_pk_bf16_f32 v237, v237, s0
	v_lshl_add_u64 v[26:27], s[98:99], 0, v[166:167]
	global_store_short v[26:27], v237, off
	v_add_f32_e32 v236, v248, v222
	v_cvt_pk_bf16_f32 v236, v236, s0
	v_lshl_add_u64 v[24:25], s[98:99], 0, v[168:169]
	global_store_short v[24:25], v236, off
	v_add_f32_e32 v237, v249, v223
	v_cvt_pk_bf16_f32 v237, v237, s0
	v_lshl_add_u64 v[26:27], s[98:99], 0, v[170:171]
	global_store_short v[26:27], v237, off
	v_add_f32_e32 v236, v250, v224
	v_cvt_pk_bf16_f32 v236, v236, s0
	v_lshl_add_u64 v[24:25], s[98:99], 0, v[172:173]
	global_store_short v[24:25], v236, off
	v_add_f32_e32 v237, v251, v225
	v_cvt_pk_bf16_f32 v237, v237, s0
	v_lshl_add_u64 v[26:27], s[98:99], 0, v[174:175]
	global_store_short v[26:27], v237, off
	v_add_f32_e32 v236, v252, v226
	v_cvt_pk_bf16_f32 v236, v236, s0
	v_lshl_add_u64 v[24:25], s[98:99], 0, v[176:177]
	global_store_short v[24:25], v236, off
	v_add_f32_e32 v237, v253, v227
	v_cvt_pk_bf16_f32 v237, v237, s0
	v_lshl_add_u64 v[26:27], s[98:99], 0, v[178:179]
	global_store_short v[26:27], v237, off
	v_add_f32_e32 v236, v254, v228
	v_cvt_pk_bf16_f32 v236, v236, s0
	v_lshl_add_u64 v[24:25], s[98:99], 0, v[180:181]
	global_store_short v[24:25], v236, off
	v_add_f32_e32 v237, v255, v229
	v_cvt_pk_bf16_f32 v237, v237, s0
	v_lshl_add_u64 v[26:27], s[98:99], 0, v[182:183]
	global_store_short v[26:27], v237, off
